# in-proj epilogue row-sum: xor-16/xor-32 lane exchanges via v_permlane16_swap/v_permlane32_swap instead of ds_bpermute + lgkmcnt(0) (bit-identical)
# baseline (speedup 1.0000x reference)
; __device__ __forceinline__ unsigned cvt_pk_bf16(float lo, float hi) { unsigned r; asm volatile("v_cvt_pk_bf16_f32 %0, %1, %2" : "=v"(r) : "v"(lo), "v"(hi)); return r; }
;     __device__ __forceinline__ void operator()(const f32x4 (&acc)[2][2][4][2], const Unit& u, int wr, int wc, int fr, int fq) const {
;     ...
;             for (int m = 0; m < 4; ++m) { const int row = row0 + ai * HALF + m * 16; const f32x4 a = pa[m], b = pb[m];
;                 float sq = ((a[0] + a[1]) + (a[2] + a[3])) + ((b[0] + b[1]) + (b[2] + b[3])); sq += __shfl_xor(sq, 16); sq += __shfl_xor(sq, 32);
;                 const float rs = __builtin_amdgcn_rsqf(sq * inv_k + eps);
; #pragma unroll
;                 for (int bj = 0; bj < 2; ++bj) { const f32x4 v0 = acc[ai][bj][m][0] * rs, v1 = acc[ai][bj][m][1] * rs;
;                     u32x4 w; w.x = cvt_pk_bf16(v0[0], v0[1]); w.y = cvt_pk_bf16(v0[2], v0[3]); w.z = cvt_pk_bf16(v1[0], v1[1]); w.w = cvt_pk_bf16(v1[2], v1[3]);
;                     *(u32x4*)(O + ((size_t)(u.pn * 2 + bj) * Mrows + row) * HALF + col0) = w; } }
.Ltail_c:
	s_ashr_i32 s15, s14, 31
	s_lshl_b64 s[34:35], s[14:15], 14
	s_or_b32 s14, s14, 1
	s_ashr_i32 s15, s14, 31
	s_lshl_b64 s[36:37], s[14:15], 14
	s_andn2_b64 vcc, exec, s[38:39]
	s_waitcnt vmcnt(0)
	v_mov_b32_e32 v190, v182
	v_mov_b32_e32 v191, v186
	v_mov_b32_e32 v186, v183
	v_pk_add_f32 v[182:183], v[190:191], v[186:187]
	v_mov_b32_e32 v186, v184
	v_mov_b32_e32 v187, v188
	v_mov_b32_e32 v188, v185
	v_pk_add_f32 v[184:185], v[186:187], v[188:189]
	s_nop 0
	v_pk_add_f32 v[182:183], v[182:183], v[184:185]
	s_nop 0
	v_add_f32_e32 v181, v182, v183
	v_mov_b32_e32 v182, v181
	s_nop 1
	v_permlane16_swap_b32_e32 v181, v182
	v_add_f32_e32 v181, v181, v182
	v_mov_b32_e32 v182, v181
	s_nop 1
	v_permlane32_swap_b32_e32 v181, v182
	v_add_f32_e32 v181, v181, v182
	v_fmamk_f32 v181, v181, 0x3a000000, v215
	v_rsq_f32_e32 v182, v181
	s_nop 0
	v_pk_mul_f32 v[142:143], v[142:143], v[182:183] op_sel_hi:[1,0]
	v_pk_mul_f32 v[184:185], v[140:141], v[182:183] op_sel_hi:[1,0]
	v_pk_mul_f32 v[140:141], v[138:139], v[182:183] op_sel_hi:[1,0]
	v_cvt_pk_bf16_f32 v138, v142, v143
	v_lshl_add_u64 v[142:143], s[34:35], 0, v[168:169]
	v_lshlrev_b64 v[142:143], 8, v[142:143]
	v_pk_mul_f32 v[144:145], v[144:145], v[182:183] op_sel_hi:[1,0]
	v_lshl_add_u64 v[142:143], v[160:161], 0, v[142:143]
	v_cvt_pk_bf16_f32 v139, v144, v145
	v_pk_mul_f32 v[126:127], v[126:127], v[182:183] op_sel_hi:[1,0]
	v_cvt_pk_bf16_f32 v140, v140, v141
	v_cvt_pk_bf16_f32 v141, v184, v185
	global_store_dwordx4 v[142:143], v[138:141], off
	v_pk_mul_f32 v[128:129], v[128:129], v[182:183] op_sel_hi:[1,0]
	s_nop 0
	v_pk_mul_f32 v[138:139], v[124:125], v[182:183] op_sel_hi:[1,0]
	v_pk_mul_f32 v[124:125], v[122:123], v[182:183] op_sel_hi:[1,0]
	v_cvt_pk_bf16_f32 v122, v126, v127
	v_lshl_add_u64 v[126:127], s[36:37], 0, v[168:169]
	v_lshlrev_b64 v[126:127], 8, v[126:127]
	v_cvt_pk_bf16_f32 v123, v128, v129
	v_cvt_pk_bf16_f32 v124, v124, v125
	v_cvt_pk_bf16_f32 v125, v138, v139
	v_lshl_add_u64 v[126:127], v[160:161], 0, v[126:127]
	s_mov_b64 exec, s[80:81]
	global_store_dwordx4 v[126:127], v[122:125], off
	s_mov_b64 exec, -1
	s_nop 1
	v_mov_b32_e32 v122, v146
	v_mov_b32_e32 v123, v150
	v_mov_b32_e32 v150, v147
	v_mov_b32_e32 v124, v148
	v_mov_b32_e32 v125, v152
	v_mov_b32_e32 v152, v149
	v_pk_add_f32 v[122:123], v[122:123], v[150:151]
	v_pk_add_f32 v[124:125], v[124:125], v[152:153]
	s_nop 0
	v_pk_add_f32 v[122:123], v[122:123], v[124:125]
	s_nop 0
	v_add_f32_e32 v122, v122, v123
	v_mov_b32_e32 v123, v122
	s_nop 1
	v_permlane16_swap_b32_e32 v122, v123
	v_add_f32_e32 v122, v122, v123
	v_mov_b32_e32 v123, v122
	s_nop 1
	v_permlane32_swap_b32_e32 v122, v123
	v_add_f32_e32 v122, v122, v123
	v_fmamk_f32 v122, v122, 0x3a000000, v215
	v_rsq_f32_e32 v122, v122
	s_nop 0
	v_pk_mul_f32 v[110:111], v[110:111], v[122:123] op_sel_hi:[1,0]
	v_pk_mul_f32 v[124:125], v[108:109], v[122:123] op_sel_hi:[1,0]
	v_pk_mul_f32 v[108:109], v[106:107], v[122:123] op_sel_hi:[1,0]
	v_cvt_pk_bf16_f32 v106, v110, v111
	v_lshl_add_u64 v[110:111], s[34:35], 0, v[174:175]
	v_lshlrev_b64 v[110:111], 8, v[110:111]
	v_pk_mul_f32 v[112:113], v[112:113], v[122:123] op_sel_hi:[1,0]
	v_lshl_add_u64 v[110:111], v[160:161], 0, v[110:111]
	v_cvt_pk_bf16_f32 v107, v112, v113
	v_pk_mul_f32 v[102:103], v[102:103], v[122:123] op_sel_hi:[1,0]
	v_cvt_pk_bf16_f32 v108, v108, v109
	v_cvt_pk_bf16_f32 v109, v124, v125
	global_store_dwordx4 v[110:111], v[106:109], off
	v_pk_mul_f32 v[104:105], v[104:105], v[122:123] op_sel_hi:[1,0]
	s_nop 0
	v_pk_mul_f32 v[106:107], v[100:101], v[122:123] op_sel_hi:[1,0]
	v_pk_mul_f32 v[100:101], v[98:99], v[122:123] op_sel_hi:[1,0]
	v_cvt_pk_bf16_f32 v98, v102, v103
	v_lshl_add_u64 v[102:103], s[36:37], 0, v[174:175]
	v_lshlrev_b64 v[102:103], 8, v[102:103]
	v_cvt_pk_bf16_f32 v99, v104, v105
	v_cvt_pk_bf16_f32 v100, v100, v101
	v_cvt_pk_bf16_f32 v101, v106, v107
	v_lshl_add_u64 v[102:103], v[160:161], 0, v[102:103]
	s_mov_b64 exec, s[80:81]
	global_store_dwordx4 v[102:103], v[98:101], off
	s_mov_b64 exec, -1
	v_add_u32_e32 v104, 0x80, v168
	v_ashrrev_i32_e32 v105, 31, v104
	v_mov_b32_e32 v98, v134
	v_mov_b32_e32 v99, v130
	v_mov_b32_e32 v130, v135
	v_mov_b32_e32 v100, v136
	v_mov_b32_e32 v101, v132
	v_mov_b32_e32 v132, v137
	v_pk_add_f32 v[98:99], v[98:99], v[130:131]
	v_pk_add_f32 v[100:101], v[100:101], v[132:133]
	s_nop 0
	v_pk_add_f32 v[98:99], v[98:99], v[100:101]
	s_nop 0
	v_add_f32_e32 v98, v98, v99
	v_mov_b32_e32 v99, v98
	s_nop 1
	v_permlane16_swap_b32_e32 v98, v99
	v_add_f32_e32 v98, v98, v99
	v_mov_b32_e32 v99, v98
	s_nop 1
	v_permlane32_swap_b32_e32 v98, v99
	v_add_f32_e32 v98, v98, v99
	v_fmamk_f32 v98, v98, 0x3a000000, v215
	v_rsq_f32_e32 v98, v98
	s_nop 0
	v_pk_mul_f32 v[94:95], v[94:95], v[98:99] op_sel_hi:[1,0]
	v_pk_mul_f32 v[100:101], v[92:93], v[98:99] op_sel_hi:[1,0]
	v_pk_mul_f32 v[92:93], v[90:91], v[98:99] op_sel_hi:[1,0]
	v_cvt_pk_bf16_f32 v90, v94, v95
	v_lshl_add_u64 v[94:95], s[34:35], 0, v[172:173]
	v_lshlrev_b64 v[94:95], 8, v[94:95]
	v_pk_mul_f32 v[96:97], v[96:97], v[98:99] op_sel_hi:[1,0]
	v_lshl_add_u64 v[94:95], v[160:161], 0, v[94:95]
	v_cvt_pk_bf16_f32 v91, v96, v97
	v_pk_mul_f32 v[86:87], v[86:87], v[98:99] op_sel_hi:[1,0]
	v_cvt_pk_bf16_f32 v92, v92, v93
	v_cvt_pk_bf16_f32 v93, v100, v101
	global_store_dwordx4 v[94:95], v[90:93], off
	v_pk_mul_f32 v[88:89], v[88:89], v[98:99] op_sel_hi:[1,0]
	s_nop 0
	v_pk_mul_f32 v[90:91], v[84:85], v[98:99] op_sel_hi:[1,0]
	v_pk_mul_f32 v[84:85], v[82:83], v[98:99] op_sel_hi:[1,0]
	v_cvt_pk_bf16_f32 v82, v86, v87
	v_lshl_add_u64 v[86:87], s[36:37], 0, v[172:173]
	v_lshlrev_b64 v[86:87], 8, v[86:87]
	v_cvt_pk_bf16_f32 v83, v88, v89
; __device__ __forceinline__ unsigned cvt_pk_bf16(float lo, float hi) { unsigned r; asm volatile("v_cvt_pk_bf16_f32 %0, %1, %2" : "=v"(r) : "v"(lo), "v"(hi)); return r; }
;     __device__ __forceinline__ void operator()(const f32x4 (&acc)[2][2][4][2], const Unit& u, int wr, int wc, int fr, int fq) const {
;     ...
;             for (int m = 0; m < 4; ++m) { const int row = row0 + ai * HALF + m * 16; const f32x4 a = pa[m], b = pb[m];
;                 float sq = ((a[0] + a[1]) + (a[2] + a[3])) + ((b[0] + b[1]) + (b[2] + b[3])); sq += __shfl_xor(sq, 16); sq += __shfl_xor(sq, 32);
;                 const float rs = __builtin_amdgcn_rsqf(sq * inv_k + eps);
; #pragma unroll
;                 for (int bj = 0; bj < 2; ++bj) { const f32x4 v0 = acc[ai][bj][m][0] * rs, v1 = acc[ai][bj][m][1] * rs;
;                     u32x4 w; w.x = cvt_pk_bf16(v0[0], v0[1]); w.y = cvt_pk_bf16(v0[2], v0[3]); w.z = cvt_pk_bf16(v1[0], v1[1]); w.w = cvt_pk_bf16(v1[2], v1[3]);
;                     *(u32x4*)(O + ((size_t)(u.pn * 2 + bj) * Mrows + row) * HALF + col0) = w; } }
	v_cvt_pk_bf16_f32 v84, v84, v85
	v_cvt_pk_bf16_f32 v85, v90, v91
	v_lshl_add_u64 v[86:87], v[160:161], 0, v[86:87]
	s_mov_b64 exec, s[80:81]
	global_store_dwordx4 v[86:87], v[82:85], off
	s_mov_b64 exec, -1
	v_add_u32_e32 v86, 0x90, v168
	v_ashrrev_i32_e32 v87, 31, v86
	v_mov_b32_e32 v82, v118
	v_mov_b32_e32 v83, v114
	v_mov_b32_e32 v114, v119
	v_mov_b32_e32 v84, v120
	v_mov_b32_e32 v85, v116
	v_mov_b32_e32 v116, v121
	v_pk_add_f32 v[82:83], v[82:83], v[114:115]
	v_pk_add_f32 v[84:85], v[84:85], v[116:117]
	s_nop 0
	v_pk_add_f32 v[82:83], v[82:83], v[84:85]
	s_nop 0
	v_add_f32_e32 v82, v82, v83
	v_mov_b32_e32 v83, v82
	s_nop 1
	v_permlane16_swap_b32_e32 v82, v83
	v_add_f32_e32 v82, v82, v83
	v_mov_b32_e32 v83, v82
	s_nop 1
	v_permlane32_swap_b32_e32 v82, v83
	v_add_f32_e32 v82, v82, v83
	v_fmamk_f32 v82, v82, 0x3a000000, v215
	v_rsq_f32_e32 v82, v82
	s_nop 0
	v_pk_mul_f32 v[78:79], v[78:79], v[82:83] op_sel_hi:[1,0]
	v_pk_mul_f32 v[84:85], v[76:77], v[82:83] op_sel_hi:[1,0]
	v_pk_mul_f32 v[76:77], v[74:75], v[82:83] op_sel_hi:[1,0]
	v_cvt_pk_bf16_f32 v74, v78, v79
	v_lshl_add_u64 v[78:79], s[34:35], 0, v[170:171]
	v_lshlrev_b64 v[78:79], 8, v[78:79]
	v_pk_mul_f32 v[80:81], v[80:81], v[82:83] op_sel_hi:[1,0]
	v_lshl_add_u64 v[78:79], v[160:161], 0, v[78:79]
	v_cvt_pk_bf16_f32 v75, v80, v81
	v_pk_mul_f32 v[70:71], v[70:71], v[82:83] op_sel_hi:[1,0]
	v_cvt_pk_bf16_f32 v76, v76, v77
	v_cvt_pk_bf16_f32 v77, v84, v85
	global_store_dwordx4 v[78:79], v[74:77], off
	v_pk_mul_f32 v[72:73], v[72:73], v[82:83] op_sel_hi:[1,0]
	v_add_u32_e32 v84, 0xa0, v168
	v_pk_mul_f32 v[74:75], v[68:69], v[82:83] op_sel_hi:[1,0]
	v_pk_mul_f32 v[68:69], v[66:67], v[82:83] op_sel_hi:[1,0]
	v_cvt_pk_bf16_f32 v66, v70, v71
	v_lshl_add_u64 v[70:71], s[36:37], 0, v[170:171]
	v_lshlrev_b64 v[70:71], 8, v[70:71]
	v_cvt_pk_bf16_f32 v67, v72, v73
	v_lshl_add_u64 v[70:71], v[160:161], 0, v[70:71]
	v_cvt_pk_bf16_f32 v68, v68, v69
	v_cvt_pk_bf16_f32 v69, v74, v75
	s_mov_b64 exec, s[80:81]
	global_store_dwordx4 v[70:71], v[66:69], off
	s_mov_b64 exec, -1
	v_ashrrev_i32_e32 v85, 31, v84
	v_add_u32_e32 v82, 0xb0, v168
	v_lshlrev_b64 v[66:67], 7, v[104:105]
	v_lshl_add_u64 v[66:67], v[162:163], 0, v[66:67]
	global_load_dwordx4 v[88:91], v[66:67], off
	global_load_dwordx4 v[92:95], v[66:67], off offset:16
	v_lshlrev_b64 v[66:67], 7, v[86:87]
	v_lshl_add_u64 v[66:67], v[162:163], 0, v[66:67]
	global_load_dwordx4 v[96:99], v[66:67], off
	global_load_dwordx4 v[100:103], v[66:67], off offset:16
	v_lshlrev_b64 v[66:67], 7, v[84:85]
	v_lshl_add_u64 v[66:67], v[162:163], 0, v[66:67]
	global_load_dwordx4 v[78:81], v[66:67], off
	global_load_dwordx4 v[74:77], v[66:67], off offset:16
	v_ashrrev_i32_e32 v83, 31, v82
	v_lshlrev_b64 v[66:67], 7, v[82:83]
	v_lshl_add_u64 v[66:67], v[162:163], 0, v[66:67]
	global_load_dwordx4 v[70:73], v[66:67], off
	s_nop 0
	global_load_dwordx4 v[66:69], v[66:67], off offset:16
	s_waitcnt vmcnt(7)
	v_mov_b32_e32 v106, v88
	s_waitcnt vmcnt(6)
	v_mov_b32_e32 v107, v92
	v_mov_b32_e32 v92, v89
	v_pk_add_f32 v[88:89], v[106:107], v[92:93]
	v_mov_b32_e32 v92, v90
	v_mov_b32_e32 v93, v94
	v_mov_b32_e32 v94, v91
	v_pk_add_f32 v[90:91], v[92:93], v[94:95]
	s_nop 0
	v_pk_add_f32 v[88:89], v[88:89], v[90:91]
	s_nop 0
	v_add_f32_e32 v88, v88, v89
	v_mov_b32_e32 v89, v88
	s_nop 1
	v_permlane16_swap_b32_e32 v88, v89
	v_add_f32_e32 v88, v88, v89
	v_mov_b32_e32 v89, v88
	s_nop 1
	v_permlane32_swap_b32_e32 v88, v89
	v_add_f32_e32 v88, v88, v89
	v_fmamk_f32 v88, v88, 0x3a000000, v215
	v_rsq_f32_e32 v88, v88
	s_nop 0
	v_pk_mul_f32 v[62:63], v[62:63], v[88:89] op_sel_hi:[1,0]
	v_pk_mul_f32 v[90:91], v[60:61], v[88:89] op_sel_hi:[1,0]
	v_pk_mul_f32 v[60:61], v[58:59], v[88:89] op_sel_hi:[1,0]
	v_cvt_pk_bf16_f32 v58, v62, v63
	v_lshl_add_u64 v[62:63], s[34:35], 0, v[104:105]
	v_lshlrev_b64 v[62:63], 8, v[62:63]
	v_pk_mul_f32 v[64:65], v[64:65], v[88:89] op_sel_hi:[1,0]
	v_lshl_add_u64 v[62:63], v[160:161], 0, v[62:63]
	v_cvt_pk_bf16_f32 v59, v64, v65
	v_pk_mul_f32 v[54:55], v[54:55], v[88:89] op_sel_hi:[1,0]
	v_cvt_pk_bf16_f32 v60, v60, v61
	v_cvt_pk_bf16_f32 v61, v90, v91
	global_store_dwordx4 v[62:63], v[58:61], off
	v_pk_mul_f32 v[56:57], v[56:57], v[88:89] op_sel_hi:[1,0]
	s_nop 0
	v_pk_mul_f32 v[58:59], v[52:53], v[88:89] op_sel_hi:[1,0]
	v_pk_mul_f32 v[52:53], v[50:51], v[88:89] op_sel_hi:[1,0]
	v_cvt_pk_bf16_f32 v50, v54, v55
	v_lshl_add_u64 v[54:55], s[36:37], 0, v[104:105]
	v_lshlrev_b64 v[54:55], 8, v[54:55]
	v_cvt_pk_bf16_f32 v51, v56, v57
	v_cvt_pk_bf16_f32 v52, v52, v53
	v_cvt_pk_bf16_f32 v53, v58, v59
	v_lshl_add_u64 v[54:55], v[160:161], 0, v[54:55]
	s_mov_b64 exec, s[80:81]
	global_store_dwordx4 v[54:55], v[50:53], off
	s_mov_b64 exec, -1
	s_waitcnt vmcnt(7)
	s_nop 0
	v_mov_b32_e32 v50, v96
	s_waitcnt vmcnt(6)
; __device__ __forceinline__ unsigned cvt_pk_bf16(float lo, float hi) { unsigned r; asm volatile("v_cvt_pk_bf16_f32 %0, %1, %2" : "=v"(r) : "v"(lo), "v"(hi)); return r; }
;     __device__ __forceinline__ void operator()(const f32x4 (&acc)[2][2][4][2], const Unit& u, int wr, int wc, int fr, int fq) const {
;     ...
;             for (int m = 0; m < 4; ++m) { const int row = row0 + ai * HALF + m * 16; const f32x4 a = pa[m], b = pb[m];
;                 float sq = ((a[0] + a[1]) + (a[2] + a[3])) + ((b[0] + b[1]) + (b[2] + b[3])); sq += __shfl_xor(sq, 16); sq += __shfl_xor(sq, 32);
;                 const float rs = __builtin_amdgcn_rsqf(sq * inv_k + eps);
; #pragma unroll
;                 for (int bj = 0; bj < 2; ++bj) { const f32x4 v0 = acc[ai][bj][m][0] * rs, v1 = acc[ai][bj][m][1] * rs;
;                     u32x4 w; w.x = cvt_pk_bf16(v0[0], v0[1]); w.y = cvt_pk_bf16(v0[2], v0[3]); w.z = cvt_pk_bf16(v1[0], v1[1]); w.w = cvt_pk_bf16(v1[2], v1[3]);
;                     *(u32x4*)(O + ((size_t)(u.pn * 2 + bj) * Mrows + row) * HALF + col0) = w; } }
	v_mov_b32_e32 v51, v100
	v_mov_b32_e32 v100, v97
	v_mov_b32_e32 v52, v98
	v_mov_b32_e32 v53, v102
	v_mov_b32_e32 v102, v99
	v_pk_add_f32 v[50:51], v[50:51], v[100:101]
	v_pk_add_f32 v[52:53], v[52:53], v[102:103]
	s_nop 0
	v_pk_add_f32 v[50:51], v[50:51], v[52:53]
	s_nop 0
	v_add_f32_e32 v50, v50, v51
	v_mov_b32_e32 v51, v50
	s_nop 1
	v_permlane16_swap_b32_e32 v50, v51
	v_add_f32_e32 v50, v50, v51
	v_mov_b32_e32 v51, v50
	s_nop 1
	v_permlane32_swap_b32_e32 v50, v51
	v_add_f32_e32 v50, v50, v51
	v_fmamk_f32 v50, v50, 0x3a000000, v215
	v_rsq_f32_e32 v50, v50
	s_nop 0
	v_pk_mul_f32 v[46:47], v[46:47], v[50:51] op_sel_hi:[1,0]
	v_pk_mul_f32 v[52:53], v[44:45], v[50:51] op_sel_hi:[1,0]
	v_pk_mul_f32 v[44:45], v[42:43], v[50:51] op_sel_hi:[1,0]
	v_cvt_pk_bf16_f32 v42, v46, v47
	v_lshl_add_u64 v[46:47], s[34:35], 0, v[86:87]
	v_lshlrev_b64 v[46:47], 8, v[46:47]
	v_pk_mul_f32 v[48:49], v[48:49], v[50:51] op_sel_hi:[1,0]
	v_lshl_add_u64 v[46:47], v[160:161], 0, v[46:47]
	v_cvt_pk_bf16_f32 v43, v48, v49
	v_pk_mul_f32 v[38:39], v[38:39], v[50:51] op_sel_hi:[1,0]
	v_cvt_pk_bf16_f32 v44, v44, v45
	v_cvt_pk_bf16_f32 v45, v52, v53
	global_store_dwordx4 v[46:47], v[42:45], off
	v_pk_mul_f32 v[40:41], v[40:41], v[50:51] op_sel_hi:[1,0]
	s_nop 0
	v_pk_mul_f32 v[42:43], v[36:37], v[50:51] op_sel_hi:[1,0]
	v_pk_mul_f32 v[36:37], v[34:35], v[50:51] op_sel_hi:[1,0]
	v_cvt_pk_bf16_f32 v34, v38, v39
	v_lshl_add_u64 v[38:39], s[36:37], 0, v[86:87]
	v_lshlrev_b64 v[38:39], 8, v[38:39]
	v_cvt_pk_bf16_f32 v35, v40, v41
	v_cvt_pk_bf16_f32 v36, v36, v37
	v_cvt_pk_bf16_f32 v37, v42, v43
	v_lshl_add_u64 v[38:39], v[160:161], 0, v[38:39]
	s_mov_b64 exec, s[80:81]
	global_store_dwordx4 v[38:39], v[34:37], off
	s_mov_b64 exec, -1
	s_waitcnt vmcnt(7)
	s_nop 0
	v_mov_b32_e32 v34, v78
	s_waitcnt vmcnt(6)
	v_mov_b32_e32 v35, v74
	v_mov_b32_e32 v74, v79
	v_mov_b32_e32 v36, v80
	v_mov_b32_e32 v37, v76
	v_mov_b32_e32 v76, v81
	v_pk_add_f32 v[34:35], v[34:35], v[74:75]
	v_pk_add_f32 v[36:37], v[36:37], v[76:77]
	s_nop 0
	v_pk_add_f32 v[34:35], v[34:35], v[36:37]
	s_nop 0
	v_add_f32_e32 v34, v34, v35
	v_mov_b32_e32 v35, v34
	s_nop 1
	v_permlane16_swap_b32_e32 v34, v35
	v_add_f32_e32 v34, v34, v35
	v_mov_b32_e32 v35, v34
	s_nop 1
	v_permlane32_swap_b32_e32 v34, v35
	v_add_f32_e32 v34, v34, v35
	v_fmamk_f32 v34, v34, 0x3a000000, v215
	v_rsq_f32_e32 v34, v34
	s_nop 0
	v_pk_mul_f32 v[30:31], v[30:31], v[34:35] op_sel_hi:[1,0]
	v_pk_mul_f32 v[36:37], v[28:29], v[34:35] op_sel_hi:[1,0]
	v_pk_mul_f32 v[28:29], v[26:27], v[34:35] op_sel_hi:[1,0]
	v_cvt_pk_bf16_f32 v26, v30, v31
	v_lshl_add_u64 v[30:31], s[34:35], 0, v[84:85]
	v_lshlrev_b64 v[30:31], 8, v[30:31]
	v_pk_mul_f32 v[32:33], v[32:33], v[34:35] op_sel_hi:[1,0]
	v_lshl_add_u64 v[30:31], v[160:161], 0, v[30:31]
	v_cvt_pk_bf16_f32 v27, v32, v33
	v_pk_mul_f32 v[22:23], v[22:23], v[34:35] op_sel_hi:[1,0]
	v_cvt_pk_bf16_f32 v28, v28, v29
	v_cvt_pk_bf16_f32 v29, v36, v37
	global_store_dwordx4 v[30:31], v[26:29], off
	v_pk_mul_f32 v[24:25], v[24:25], v[34:35] op_sel_hi:[1,0]
	s_nop 0
	v_pk_mul_f32 v[26:27], v[20:21], v[34:35] op_sel_hi:[1,0]
	v_pk_mul_f32 v[20:21], v[18:19], v[34:35] op_sel_hi:[1,0]
	v_cvt_pk_bf16_f32 v18, v22, v23
	v_lshl_add_u64 v[22:23], s[36:37], 0, v[84:85]
	v_lshlrev_b64 v[22:23], 8, v[22:23]
	v_cvt_pk_bf16_f32 v19, v24, v25
	v_cvt_pk_bf16_f32 v20, v20, v21
	v_cvt_pk_bf16_f32 v21, v26, v27
	v_lshl_add_u64 v[22:23], v[160:161], 0, v[22:23]
	s_mov_b64 exec, s[80:81]
	global_store_dwordx4 v[22:23], v[18:21], off
	s_mov_b64 exec, -1
	s_waitcnt vmcnt(7)
	s_nop 0
	v_mov_b32_e32 v18, v70
	s_waitcnt vmcnt(6)
	v_mov_b32_e32 v19, v66
	v_mov_b32_e32 v66, v71
	v_mov_b32_e32 v20, v72
	v_mov_b32_e32 v21, v68
	v_mov_b32_e32 v68, v73
	v_pk_add_f32 v[18:19], v[18:19], v[66:67]
	v_pk_add_f32 v[20:21], v[20:21], v[68:69]
	s_nop 0
	v_pk_add_f32 v[18:19], v[18:19], v[20:21]
	s_nop 0
	v_add_f32_e32 v18, v18, v19
	v_mov_b32_e32 v19, v18
	s_nop 1
	v_permlane16_swap_b32_e32 v18, v19
	v_add_f32_e32 v18, v18, v19
	v_mov_b32_e32 v19, v18
	s_nop 1
	v_permlane32_swap_b32_e32 v18, v19
	v_add_f32_e32 v18, v18, v19
	v_fmamk_f32 v18, v18, 0x3a000000, v215
	v_rsq_f32_e32 v18, v18
	s_nop 0
	v_pk_mul_f32 v[14:15], v[14:15], v[18:19] op_sel_hi:[1,0]
	v_pk_mul_f32 v[20:21], v[12:13], v[18:19] op_sel_hi:[1,0]
	v_pk_mul_f32 v[12:13], v[10:11], v[18:19] op_sel_hi:[1,0]
	v_cvt_pk_bf16_f32 v10, v14, v15
	v_lshl_add_u64 v[14:15], s[34:35], 0, v[82:83]
	v_lshlrev_b64 v[14:15], 8, v[14:15]
	v_pk_mul_f32 v[16:17], v[16:17], v[18:19] op_sel_hi:[1,0]
	v_lshl_add_u64 v[14:15], v[160:161], 0, v[14:15]
	v_cvt_pk_bf16_f32 v11, v16, v17
	v_pk_mul_f32 v[6:7], v[6:7], v[18:19] op_sel_hi:[1,0]
	v_cvt_pk_bf16_f32 v12, v12, v13
	v_cvt_pk_bf16_f32 v13, v20, v21
	global_store_dwordx4 v[14:15], v[10:13], off
	v_pk_mul_f32 v[8:9], v[8:9], v[18:19] op_sel_hi:[1,0]
	s_mov_b64 s[34:35], -1
	v_pk_mul_f32 v[10:11], v[4:5], v[18:19] op_sel_hi:[1,0]
	v_pk_mul_f32 v[4:5], v[2:3], v[18:19] op_sel_hi:[1,0]
	v_cvt_pk_bf16_f32 v2, v6, v7
	v_lshl_add_u64 v[6:7], s[36:37], 0, v[82:83]
	v_lshlrev_b64 v[6:7], 8, v[6:7]
	v_lshl_add_u64 v[6:7], v[160:161], 0, v[6:7]
	v_cvt_pk_bf16_f32 v3, v8, v9
	v_cvt_pk_bf16_f32 v4, v4, v5
	v_cvt_pk_bf16_f32 v5, v10, v11
	s_mov_b64 exec, s[80:81]
	global_store_dwordx4 v[6:7], v[2:5], off
	s_mov_b64 exec, -1
	s_cbranch_vccnz .LBB0_210
	s_andn2_b64 vcc, exec, s[0:1]
	s_cbranch_vccnz .LBB0_209
	s_barrier
	s_branch .LBB0_209
